# sample_prep task: L2 warm-up of its weight rows (one 128-B line per row and workgroup, LDS-DMA into an unused LDS line) issued at task start
# baseline (speedup 1.0000x reference)
; DEV bf16_t f2bf(float f) { unsigned u = __float_as_uint(f); u += 0x7fffu + ((u >> 16) & 1u); return (bf16_t)(u >> 16); }
; DEV float sigmoidf_(float x) { return __builtin_amdgcn_rcpf(1.f + fexp(-x)); }
; DEV float gelu_tanh(float x) { const float u = 0.7978845608028654f * (x + 0.044715f * x * x * x); return x * sigmoidf_(2.f * u); }
; DEV void sample_prep_task(int l, int b, int t, LAS unsigned char* sm, unsigned char* ws, float* out, const SampleW& w, const bf16_t* wqb, const bf16_t* wglu) {
;     ...
;     const int lane = t & 63, wv = t >> 6; const bool act = t < 256;
;     const float* ps = (const float*)(ws + WS_PS) + (size_t)b * DINP;
;     bf16_t* mixs = (bf16_t*)(ws + WS_MIXS) + (size_t)b * DM;
;     __syncthreads();
;     float cq = 0.f, t2 = 0.f;
;     if (act) { u[t] = ps[t]; cq = ps[256 + t]; t2 = ps[512 + t];
;         const float s1 = wave_sum(cq * cq), s2 = wave_sum(t < 128 ? t2 * t2 : 0.f);
;         if (lane == 0) { red[wv] = s1; red[4 + wv] = s2; } }
;     __syncthreads();
;     const float rq = rsqrtf(((red[0] + red[1]) + (red[2] + red[3])) * (1.f / 256.f) + EPS), rk = rsqrtf(((red[4] + red[5]) + (red[6] + red[7])) * (1.f / 128.f) + EPS);
;     ...
;     qv[t] = dot_bf16row<256>(wqb + (size_t)t * 256, cqn);
;     if (act) { const int g = t >> 4, c = t & 15; const float* cr = w.s5_c_re + (((size_t)l * 16 + g) * 16 + c) * 64; const float* ci = w.s5_c_im + (((size_t)l * 16 + g) * 16 + c) * 64;
;         const float y = dot_f32row<64>(cr, hsr + g * 64) - dot_f32row<64>(ci, hsi + g * 64) + w.s5_d[l * 256 + t] * u[t]; ys[t] = gelu_tanh(y); }
;     else qv[256 + t] = dot_bf16row<256>(wqb + (size_t)(256 + t) * 256, cqn);
;     __syncthreads();
;     float* qlat = (float*)(ws + WS_QLAT) + (size_t)b * MH * 160;
; #pragma unroll
;     for (int i = 0; i < 2; ++i) { const int idx = t + 512 * i, h = idx >> 7, lp = idx & 127;
;         qlat[h * 160 + lp] = dot_f32row<64>(w.w_uk + (((size_t)l * 128 + lp) * 8 + h) * 64, qv + h * 64) * QSCALE; }
;     if (act) { const float z = dot_bf16row<256>(wglu + (size_t)t * 256, ys) + w.s5_b_glu[l * 256 + t]; mixs[t] = f2bf(ys[t] * sigmoidf_(z));
.LBB0_1026:
	v_readlane_b32 s98, v254, 0
	s_lshr_b32 s98, s98, 3
	s_and_b32 s98, s98, 3
	s_and_b32 s72, s98, 1
	s_lshl_b32 s98, s98, 7
	s_lshl_b32 s72, s72, 7
	s_sub_i32 s98, s98, 0x70
	s_sub_i32 s72, s72, 0x70
	s_ashr_i32 s99, s98, 31
	s_ashr_i32 s73, s72, 31
	s_mov_b32 s84, m0
	s_add_i32 s28, s96, 0x18000
	s_mov_b32 m0, s28
	v_and_b32_e32 v111, 0xff, v114
	v_add_u32_e32 v111, 0x200, v111
	v_lshlrev_b32_e32 v111, 9, v111
	v_lshl_add_u64 v[92:93], s[58:59], 0, v[76:77]
	v_lshl_add_u64 v[92:93], v[92:93], 0, s[98:99]
	global_load_lds_dword v[92:93], off
	v_mov_b32_e32 v92, v111
	v_mov_b32_e32 v93, 0
	v_lshl_add_u64 v[92:93], s[58:59], 0, v[92:93]
	v_lshl_add_u64 v[92:93], v[92:93], 0, s[98:99]
	global_load_lds_dword v[92:93], off
	v_lshl_add_u64 v[92:93], v[82:83], 0, s[72:73]
	global_load_lds_dword v[92:93], off
	v_lshl_add_u64 v[92:93], v[84:85], 0, s[72:73]
	global_load_lds_dword v[92:93], off
	s_mov_b64 s[82:83], exec
	s_and_b64 exec, exec, s[4:5]
	v_lshl_add_u64 v[92:93], v[78:79], 0, s[72:73]
	global_load_lds_dword v[92:93], off
	v_lshl_add_u64 v[92:93], v[80:81], 0, s[72:73]
	global_load_lds_dword v[92:93], off
	v_lshl_add_u64 v[92:93], s[60:61], 0, v[76:77]
	v_lshl_add_u64 v[92:93], v[92:93], 0, s[98:99]
	global_load_lds_dword v[92:93], off
	s_mov_b64 exec, s[82:83]
	s_mov_b32 m0, s84
	s_mul_i32 s28, s40, 0x1800
	s_mul_hi_i32 s1, s40, 0x1800
	s_add_u32 s70, s36, s28
	s_addc_u32 s71, s37, s1
	v_mov_b32_e32 v111, 0
	v_lshl_add_u64 v[92:93], v[114:115], 2, s[70:71]
	v_mov_b32_e32 v2, 0
	s_barrier
	s_and_saveexec_b64 s[28:29], s[4:5]
	s_cbranch_execz .LBB0_1030
	global_load_dword v2, v[92:93], off
	s_waitcnt vmcnt(0)
	ds_write_b32 v100, v2
	global_load_dword v2, v[92:93], off offset:1024
	global_load_dword v111, v[92:93], off offset:2048
	v_mbcnt_lo_u32_b32 v4, -1, 0
	v_mbcnt_hi_u32_b32 v4, -1, v4
	s_waitcnt vmcnt(1)
	v_mul_f32_e32 v3, v2, v2
	v_lshlrev_b32_e32 v4, 2, v4
	v_xor_b32_e32 v4, 4, v4
	ds_bpermute_b32 v3, v4, v3
	v_mbcnt_lo_u32_b32 v4, -1, 0
	v_mbcnt_hi_u32_b32 v4, -1, v4
	s_waitcnt vmcnt(0)
	v_mul_f32_e32 v5, v111, v111
	v_lshlrev_b32_e32 v4, 2, v4
	v_xor_b32_e32 v4, 8, v4
	s_waitcnt lgkmcnt(0)
	v_fmac_f32_e32 v3, v2, v2
	ds_bpermute_b32 v4, v4, v3
	v_cndmask_b32_e64 v5, 0, v5, s[8:9]
	s_waitcnt lgkmcnt(0)
	v_add_f32_e32 v3, v3, v4
	v_mbcnt_lo_u32_b32 v4, -1, 0
	v_mbcnt_hi_u32_b32 v4, -1, v4
	s_nop 0
	v_lshlrev_b32_e32 v4, 2, v4
	v_xor_b32_e32 v4, 16, v4
	ds_bpermute_b32 v4, v4, v3
	s_waitcnt lgkmcnt(0)
	v_add_f32_e32 v3, v3, v4
	v_mbcnt_lo_u32_b32 v4, -1, 0
	v_mbcnt_hi_u32_b32 v4, -1, v4
	s_nop 0
	v_lshlrev_b32_e32 v4, 2, v4
	v_xor_b32_e32 v4, 32, v4
	ds_bpermute_b32 v4, v4, v3
	s_waitcnt lgkmcnt(0)
	v_add_f32_e32 v3, v3, v4
	v_mbcnt_lo_u32_b32 v4, -1, 0
	v_mbcnt_hi_u32_b32 v4, -1, v4
	s_nop 0
	v_lshlrev_b32_e32 v4, 2, v4
	v_xor_b32_e32 v4, 64, v4
	ds_bpermute_b32 v4, v4, v3
	s_waitcnt lgkmcnt(0)
	v_add_f32_e32 v3, v3, v4
	v_mbcnt_lo_u32_b32 v4, -1, 0
	v_mbcnt_hi_u32_b32 v4, -1, v4
	v_mbcnt_lo_u32_b32 v6, -1, 0
	v_mbcnt_hi_u32_b32 v6, -1, v6
	s_nop 0
	v_lshlrev_b32_e32 v6, 2, v6
	v_xor_b32_e32 v6, 4, v6
	ds_bpermute_b32 v6, v6, v5
	v_lshlrev_b32_e32 v4, 2, v4
	v_xor_b32_e32 v4, 0x80, v4
	ds_bpermute_b32 v4, v4, v3
	s_waitcnt lgkmcnt(1)
	v_add_f32_e32 v5, v5, v6
	v_mbcnt_lo_u32_b32 v6, -1, 0
	v_mbcnt_hi_u32_b32 v6, -1, v6
	s_nop 0
	v_lshlrev_b32_e32 v6, 2, v6
	v_xor_b32_e32 v6, 8, v6
	ds_bpermute_b32 v6, v6, v5
	s_waitcnt lgkmcnt(0)
	v_add_f32_e32 v5, v5, v6
	v_mbcnt_lo_u32_b32 v6, -1, 0
	v_mbcnt_hi_u32_b32 v6, -1, v6
	s_nop 0
	v_lshlrev_b32_e32 v6, 2, v6
	v_xor_b32_e32 v6, 16, v6
	ds_bpermute_b32 v6, v6, v5
	s_waitcnt lgkmcnt(0)
	v_add_f32_e32 v5, v5, v6
	v_mbcnt_lo_u32_b32 v6, -1, 0
	v_mbcnt_hi_u32_b32 v6, -1, v6
	s_nop 0
	v_lshlrev_b32_e32 v6, 2, v6
	v_xor_b32_e32 v6, 32, v6
	ds_bpermute_b32 v6, v6, v5
	s_waitcnt lgkmcnt(0)
	v_add_f32_e32 v5, v5, v6
	v_mbcnt_lo_u32_b32 v6, -1, 0
	v_mbcnt_hi_u32_b32 v6, -1, v6
	s_nop 0
	v_lshlrev_b32_e32 v6, 2, v6
	v_xor_b32_e32 v6, 64, v6
	ds_bpermute_b32 v6, v6, v5
	s_waitcnt lgkmcnt(0)
	v_add_f32_e32 v5, v5, v6
	v_mbcnt_lo_u32_b32 v6, -1, 0
	v_mbcnt_hi_u32_b32 v6, -1, v6
	s_nop 0
	v_lshlrev_b32_e32 v6, 2, v6
	v_xor_b32_e32 v6, 0x80, v6
	ds_bpermute_b32 v6, v6, v5
	s_and_saveexec_b64 s[44:45], s[12:13]
	s_cbranch_execz .LBB0_1029
	v_add_f32_e32 v3, v3, v4
	s_waitcnt lgkmcnt(0)
	v_add_f32_e32 v4, v5, v6
	ds_write2_b32 v109, v3, v4 offset1:4
